# L2 residency in the mixer: streaming accesses (short-conv loads/stores, weight-conversion loads/stores) marked non-temporal so they do not evict the K/V rows reused by attention (timing-only)
# speedup vs baseline: 1.0687x; 1.0687x over previous
.LBB0_113:
	s_nop 0
	v_lshl_add_u64 v[34:35], s[34:35], 0, v[0:1]
	v_add_co_u32_e32 v36, vcc, 0x7100000, v34
	s_mov_b32 s4, 0x7100000
	s_nop 0
	v_addc_co_u32_e32 v37, vcc, 0, v35, vcc
	v_add_co_u32_e32 v34, vcc, 0x7101000, v34
	global_load_dwordx4 v[70:73], v[36:37], off offset:3072 nt
	s_nop 0
	v_addc_co_u32_e32 v35, vcc, 0, v35, vcc
	global_load_dwordx4 v[78:81], v[34:35], off nt
	global_load_dwordx4 v[74:77], v[34:35], off offset:1024 nt
	v_lshl_add_u64 v[34:35], s[28:29], 0, v[0:1]
	v_add_co_u32_e32 v36, vcc, s4, v34
	s_mov_b32 s4, 0x7101000
	s_nop 0
	v_addc_co_u32_e32 v37, vcc, 0, v35, vcc
	v_add_co_u32_e32 v34, vcc, s4, v34
	global_load_dwordx4 v[58:61], v[36:37], off offset:3072 nt
	s_nop 0
	v_addc_co_u32_e32 v35, vcc, 0, v35, vcc
	global_load_dwordx4 v[66:69], v[34:35], off nt
	global_load_dwordx4 v[62:65], v[34:35], off offset:1024 nt
	s_add_i32 s42, s24, 2
	v_mad_i64_i32 v[34:35], s[4:5], s42, v245, v[82:83]
	global_load_dwordx4 v[38:41], v[34:35], off offset:3072 nt
	v_add_co_u32_e32 v34, vcc, s45, v34
	s_add_i32 s36, s24, 3
	s_nop 0
	v_addc_co_u32_e32 v35, vcc, 0, v35, vcc
	global_load_dwordx4 v[54:57], v[34:35], off nt
	global_load_dwordx4 v[50:53], v[34:35], off offset:1024 nt
	v_mad_i64_i32 v[42:43], s[4:5], s36, v245, v[82:83]
	global_load_dwordx4 v[34:37], v[42:43], off offset:3072 nt
	v_add_co_u32_e32 v42, vcc, s45, v42
	s_ashr_i32 s43, s42, 31
	s_nop 0
	v_addc_co_u32_e32 v43, vcc, 0, v43, vcc
	global_load_dwordx4 v[46:49], v[42:43], off nt
	s_nop 0
	global_load_dwordx4 v[42:45], v[42:43], off offset:1024 nt
	s_lshl_b64 s[4:5], s[42:43], 11
	s_ashr_i32 s37, s36, 31
	s_add_i32 s24, s24, 4
	s_waitcnt vmcnt(11)
	v_lshlrev_b32_e32 v104, 16, v73
	v_and_b32_e32 v105, 0xffff0000, v73
	s_waitcnt vmcnt(10)
	v_lshlrev_b32_e32 v102, 16, v81
	v_and_b32_e32 v103, 0xffff0000, v81
	s_waitcnt vmcnt(9)
	v_lshlrev_b32_e32 v110, 16, v77
	v_and_b32_e32 v111, 0xffff0000, v77
	v_pk_mul_f32 v[102:103], v[102:103], v[110:111]
	v_pk_mul_f32 v[110:111], v[12:13], v[96:97]
	v_and_b32_e32 v73, 0xffff0000, v80
	v_pk_fma_f32 v[100:101], v[4:5], v[100:101], v[110:111]
	v_lshlrev_b32_e32 v110, 16, v72
	v_and_b32_e32 v111, 0xffff0000, v72
	v_lshlrev_b32_e32 v72, 16, v80
	v_lshlrev_b32_e32 v80, 16, v76
	v_and_b32_e32 v81, 0xffff0000, v76
	v_pk_mul_f32 v[76:77], v[10:11], v[92:93]
	v_pk_mul_f32 v[72:73], v[72:73], v[80:81]
	v_pk_fma_f32 v[76:77], v[2:3], v[98:99], v[76:77]
	v_lshlrev_b32_e32 v114, 16, v75
	v_pk_fma_f32 v[76:77], v[22:23], v[72:73], v[76:77]
	v_and_b32_e32 v115, 0xffff0000, v75
	v_pk_mul_f32 v[80:81], v[76:77], v[110:111]
	v_lshlrev_b32_e32 v76, 16, v79
	v_and_b32_e32 v77, 0xffff0000, v79
	v_pk_mul_f32 v[76:77], v[76:77], v[114:115]
	v_pk_mul_f32 v[114:115], v[16:17], v[90:91]
	v_lshlrev_b32_e32 v98, 16, v71
	v_pk_fma_f32 v[94:95], v[8:9], v[94:95], v[114:115] op_sel:[0,1,0] op_sel_hi:[1,0,1]
	v_and_b32_e32 v99, 0xffff0000, v71
	v_pk_fma_f32 v[94:95], v[20:21], v[76:77], v[94:95]
	v_and_b32_e32 v71, 0xffff0000, v78
	v_pk_mul_f32 v[94:95], v[94:95], v[98:99]
	v_lshlrev_b32_e32 v98, 16, v70
	v_and_b32_e32 v99, 0xffff0000, v70
	v_lshlrev_b32_e32 v70, 16, v78
	v_lshlrev_b32_e32 v78, 16, v74
	v_and_b32_e32 v79, 0xffff0000, v74
	v_pk_mul_f32 v[74:75], v[14:15], v[88:89]
	v_pk_mul_f32 v[70:71], v[70:71], v[78:79]
	v_pk_fma_f32 v[74:75], v[6:7], v[86:87], v[74:75] op_sel:[0,1,0] op_sel_hi:[1,0,1]
	s_waitcnt vmcnt(6)
	v_lshlrev_b32_e32 v118, 16, v65
	v_pk_fma_f32 v[74:75], v[18:19], v[70:71], v[74:75]
	v_and_b32_e32 v119, 0xffff0000, v65
	v_pk_mul_f32 v[78:79], v[74:75], v[98:99]
	v_lshlrev_b32_e32 v74, 16, v69
	v_and_b32_e32 v75, 0xffff0000, v69
	v_pk_mul_f32 v[74:75], v[74:75], v[118:119]
	v_pk_mul_f32 v[118:119], v[12:13], v[102:103]
	v_lshlrev_b32_e32 v86, 16, v61
	v_and_b32_e32 v87, 0xffff0000, v61
	v_pk_fma_f32 v[96:97], v[4:5], v[96:97], v[118:119]
	v_lshlrev_b32_e32 v118, 16, v60
	v_and_b32_e32 v119, 0xffff0000, v60
	v_lshlrev_b32_e32 v60, 16, v68
	v_and_b32_e32 v61, 0xffff0000, v68
	v_lshlrev_b32_e32 v68, 16, v64
	v_and_b32_e32 v69, 0xffff0000, v64
	v_pk_mul_f32 v[64:65], v[10:11], v[72:73]
	v_pk_mul_f32 v[60:61], v[60:61], v[68:69]
	v_pk_fma_f32 v[64:65], v[2:3], v[92:93], v[64:65]
	v_lshlrev_b32_e32 v120, 16, v63
	v_pk_fma_f32 v[64:65], v[22:23], v[60:61], v[64:65]
	v_and_b32_e32 v121, 0xffff0000, v63
	v_pk_mul_f32 v[68:69], v[64:65], v[118:119]
	v_lshlrev_b32_e32 v64, 16, v67
	v_and_b32_e32 v65, 0xffff0000, v67
	v_pk_mul_f32 v[64:65], v[64:65], v[120:121]
	v_pk_mul_f32 v[120:121], v[16:17], v[76:77]
	v_lshlrev_b32_e32 v118, 16, v59
	v_and_b32_e32 v119, 0xffff0000, v59
	v_pk_fma_f32 v[90:91], v[8:9], v[90:91], v[120:121]
	v_lshlrev_b32_e32 v120, 16, v58
	v_and_b32_e32 v121, 0xffff0000, v58
	v_lshlrev_b32_e32 v58, 16, v66
	v_and_b32_e32 v59, 0xffff0000, v66
	v_lshlrev_b32_e32 v66, 16, v62
	v_and_b32_e32 v67, 0xffff0000, v62
	v_pk_mul_f32 v[62:63], v[14:15], v[70:71]
	v_pk_mul_f32 v[58:59], v[58:59], v[66:67]
	v_pk_fma_f32 v[62:63], v[6:7], v[88:89], v[62:63]
	v_pk_fma_f32 v[90:91], v[20:21], v[64:65], v[90:91]
	v_pk_fma_f32 v[62:63], v[18:19], v[58:59], v[62:63]
	v_pk_mul_f32 v[116:117], v[78:79], v[78:79]
	v_pk_mul_f32 v[62:63], v[62:63], v[120:121]
	v_pk_mul_f32 v[90:91], v[90:91], v[118:119]
	v_pk_mul_f32 v[66:67], v[62:63], v[62:63]
	v_pk_mul_f32 v[114:115], v[94:95], v[94:95]
	v_pk_mul_f32 v[118:119], v[90:91], v[90:91]
	v_mov_b32_e32 v88, v66
	v_mov_b32_e32 v89, v116
	v_mov_b32_e32 v116, v67
	v_pk_add_f32 v[66:67], v[88:89], v[116:117]
	v_mov_b32_e32 v88, v118
	v_mov_b32_e32 v89, v114
	v_pk_fma_f32 v[100:101], v[24:25], v[102:103], v[100:101]
	v_pk_mul_f32 v[110:111], v[80:81], v[80:81]
	v_pk_fma_f32 v[96:97], v[24:25], v[74:75], v[96:97]
	v_pk_mul_f32 v[92:93], v[68:69], v[68:69]
	v_pk_add_f32 v[66:67], v[88:89], v[66:67]
	v_mov_b32_e32 v114, v119
	v_pk_mul_f32 v[100:101], v[100:101], v[104:105]
	v_pk_mul_f32 v[86:87], v[96:97], v[86:87]
	v_pk_add_f32 v[66:67], v[114:115], v[66:67]
	v_mov_b32_e32 v88, v92
	v_mov_b32_e32 v89, v110
	v_pk_mul_f32 v[104:105], v[100:101], v[100:101]
	v_pk_mul_f32 v[96:97], v[86:87], v[86:87]
	v_pk_add_f32 v[66:67], v[88:89], v[66:67]
	v_mov_b32_e32 v110, v93
	v_pk_add_f32 v[66:67], v[110:111], v[66:67]
	v_mov_b32_e32 v88, v96
	v_mov_b32_e32 v89, v104
	v_pk_add_f32 v[66:67], v[88:89], v[66:67]
	v_mov_b32_e32 v104, v97
	v_pk_add_f32 v[66:67], v[104:105], v[66:67]
	ds_bpermute_b32 v89, v106, v67
	ds_bpermute_b32 v88, v106, v66
	v_mov_b64_e32 v[104:105], s[44:45]
	v_lshl_add_u64 v[98:99], s[30:31], 0, v[0:1]
	s_waitcnt lgkmcnt(0)
	v_pk_add_f32 v[66:67], v[66:67], v[88:89]
	ds_bpermute_b32 v89, v107, v67
	ds_bpermute_b32 v88, v107, v66
	s_waitcnt lgkmcnt(0)
	v_pk_add_f32 v[66:67], v[66:67], v[88:89]
	ds_bpermute_b32 v89, v108, v67
	ds_bpermute_b32 v88, v108, v66
	s_waitcnt lgkmcnt(0)
	v_pk_add_f32 v[66:67], v[66:67], v[88:89]
	s_nop 0
	v_pk_fma_f32 v[66:67], v[66:67], s[46:47], v[104:105] op_sel_hi:[1,0,0]
	s_nop 0
	v_mul_f32_e32 v88, 0x4b800000, v67
	v_cmp_gt_f32_e64 s[40:41], s10, v67
	v_cmp_gt_f32_e32 vcc, s10, v66
	s_nop 0
	v_cndmask_b32_e64 v67, v67, v88, s[40:41]
	v_rsq_f32_e32 v67, v67
	s_nop 0
	v_mul_f32_e32 v88, 0x45800000, v67
	v_cndmask_b32_e64 v88, v67, v88, s[40:41]
	v_mul_f32_e32 v67, 0x4b800000, v66
	v_cndmask_b32_e32 v66, v66, v67, vcc
	v_rsq_f32_e32 v66, v66
	v_pk_mul_f32 v[78:79], v[78:79], v[88:89] op_sel_hi:[1,0]
	v_pk_mul_f32 v[92:93], v[94:95], v[88:89] op_sel_hi:[1,0]
	v_pk_mul_f32 v[80:81], v[80:81], v[88:89] op_sel_hi:[1,0]
	v_pk_mul_f32 v[88:89], v[100:101], v[88:89] op_sel_hi:[1,0]
	v_pk_mul_f32 v[78:79], v[30:31], v[78:79]
	v_pk_mul_f32 v[92:93], v[32:33], v[92:93]
	v_pk_mul_f32 v[80:81], v[26:27], v[80:81]
	v_pk_mul_f32 v[88:89], v[28:29], v[88:89]
	v_cvt_pk_bf16_f32 v78, v78, v79
	v_cvt_pk_bf16_f32 v79, v92, v93
	v_cvt_pk_bf16_f32 v80, v80, v81
	v_cvt_pk_bf16_f32 v81, v88, v89
	v_mul_f32_e32 v67, 0x45800000, v66
	global_store_dwordx4 v[98:99], v[78:81], off nt
	s_nop 1
	v_cndmask_b32_e32 v78, v66, v67, vcc
	v_pk_mul_f32 v[62:63], v[62:63], v[78:79] op_sel_hi:[1,0]
	s_nop 0
	v_pk_mul_f32 v[62:63], v[30:31], v[62:63]
	s_nop 0
	v_cvt_pk_bf16_f32 v66, v62, v63
	v_pk_mul_f32 v[62:63], v[90:91], v[78:79] op_sel_hi:[1,0]
	s_nop 0
	v_pk_mul_f32 v[62:63], v[32:33], v[62:63]
	s_nop 0
	v_cvt_pk_bf16_f32 v67, v62, v63
	v_pk_mul_f32 v[62:63], v[68:69], v[78:79] op_sel_hi:[1,0]
	s_nop 0
	v_pk_mul_f32 v[62:63], v[26:27], v[62:63]
	s_nop 0
	v_cvt_pk_bf16_f32 v68, v62, v63
	v_pk_mul_f32 v[62:63], v[86:87], v[78:79] op_sel_hi:[1,0]
	s_nop 0
	v_pk_mul_f32 v[62:63], v[28:29], v[62:63]
	s_nop 0
	v_cvt_pk_bf16_f32 v69, v62, v63
	v_lshl_add_u64 v[62:63], s[26:27], 0, v[0:1]
	global_store_dwordx4 v[62:63], v[66:69], off nt
	s_waitcnt vmcnt(6)
	v_and_b32_e32 v62, 0xffff0000, v54
	v_lshlrev_b32_e32 v63, 16, v54
	s_waitcnt vmcnt(5)
	v_and_b32_e32 v66, 0xffff0000, v50
	v_lshlrev_b32_e32 v67, 16, v50
	v_and_b32_e32 v54, 0xffff0000, v55
	v_lshlrev_b32_e32 v55, 16, v55
	v_and_b32_e32 v50, 0xffff0000, v51
	v_lshlrev_b32_e32 v51, 16, v51
	v_pk_mul_f32 v[94:95], v[54:55], v[50:51]
	v_lshlrev_b32_e32 v50, 16, v56
	v_and_b32_e32 v51, 0xffff0000, v56
	v_lshlrev_b32_e32 v54, 16, v52
	v_and_b32_e32 v55, 0xffff0000, v52
	v_pk_mul_f32 v[98:99], v[50:51], v[54:55]
	v_lshlrev_b32_e32 v50, 16, v57
	v_and_b32_e32 v51, 0xffff0000, v57
	v_lshlrev_b32_e32 v52, 16, v53
	v_and_b32_e32 v53, 0xffff0000, v53
	v_pk_mul_f32 v[86:87], v[62:63], v[66:67]
	v_pk_mul_f32 v[100:101], v[50:51], v[52:53]
	v_lshlrev_b32_e32 v50, 16, v41
	v_and_b32_e32 v51, 0xffff0000, v41
	v_lshlrev_b32_e32 v54, 16, v40
	v_and_b32_e32 v55, 0xffff0000, v40
	v_pk_mul_f32 v[40:41], v[10:11], v[60:61]
	v_lshlrev_b32_e32 v56, 16, v39
	v_and_b32_e32 v57, 0xffff0000, v39
	v_lshlrev_b32_e32 v66, 16, v38
	v_and_b32_e32 v67, 0xffff0000, v38
	v_pk_mul_f32 v[38:39], v[14:15], v[58:59]
	v_pk_fma_f32 v[40:41], v[2:3], v[72:73], v[40:41]
	v_pk_fma_f32 v[38:39], v[6:7], v[70:71], v[38:39]
	s_waitcnt vmcnt(3)
	v_lshlrev_b32_e32 v70, 16, v46
	v_and_b32_e32 v71, 0xffff0000, v46
	s_waitcnt vmcnt(2)
	v_lshlrev_b32_e32 v72, 16, v42
	v_and_b32_e32 v73, 0xffff0000, v42
	v_lshlrev_b32_e32 v46, 16, v47
	v_and_b32_e32 v47, 0xffff0000, v47
	v_lshlrev_b32_e32 v42, 16, v43
	v_and_b32_e32 v43, 0xffff0000, v43
	v_pk_mul_f32 v[90:91], v[46:47], v[42:43]
	v_lshlrev_b32_e32 v42, 16, v48
	v_and_b32_e32 v43, 0xffff0000, v48
	v_lshlrev_b32_e32 v46, 16, v44
	v_and_b32_e32 v47, 0xffff0000, v44
	v_pk_mul_f32 v[92:93], v[42:43], v[46:47]
	v_lshlrev_b32_e32 v42, 16, v49
	v_and_b32_e32 v43, 0xffff0000, v49
	v_lshlrev_b32_e32 v44, 16, v45
	v_and_b32_e32 v45, 0xffff0000, v45
	v_pk_mul_f32 v[96:97], v[42:43], v[44:45]
	v_lshlrev_b32_e32 v42, 16, v37
	v_and_b32_e32 v43, 0xffff0000, v37
	v_lshlrev_b32_e32 v46, 16, v36
	v_and_b32_e32 v47, 0xffff0000, v36
	v_pk_mul_f32 v[36:37], v[10:11], v[98:99]
	v_pk_mul_f32 v[62:63], v[16:17], v[64:65]
	v_pk_fma_f32 v[36:37], v[2:3], v[60:61], v[36:37]
	v_pk_mul_f32 v[60:61], v[16:17], v[94:95] op_sel:[0,1] op_sel_hi:[1,0]
	v_lshlrev_b32_e32 v48, 16, v35
	v_and_b32_e32 v49, 0xffff0000, v35
	v_pk_fma_f32 v[60:61], v[8:9], v[64:65], v[60:61]
	v_lshlrev_b32_e32 v64, 16, v34
	v_and_b32_e32 v65, 0xffff0000, v34
	v_pk_mul_f32 v[34:35], v[14:15], v[86:87] op_sel:[0,1] op_sel_hi:[1,0]
	v_pk_mul_f32 v[88:89], v[70:71], v[72:73]
	v_pk_fma_f32 v[34:35], v[6:7], v[58:59], v[34:35]
	v_pk_fma_f32 v[62:63], v[8:9], v[76:77], v[62:63]
	v_pk_fma_f32 v[38:39], v[18:19], v[86:87], v[38:39] op_sel:[0,1,0] op_sel_hi:[1,0,1]
	v_pk_fma_f32 v[34:35], v[18:19], v[88:89], v[34:35]
	v_pk_fma_f32 v[62:63], v[20:21], v[94:95], v[62:63] op_sel:[0,1,0] op_sel_hi:[1,0,1]
	v_pk_mul_f32 v[38:39], v[38:39], v[66:67]
	v_pk_fma_f32 v[60:61], v[20:21], v[90:91], v[60:61]
	v_pk_mul_f32 v[58:59], v[34:35], v[64:65]
	v_pk_mul_f32 v[56:57], v[62:63], v[56:57]
	v_pk_mul_f32 v[66:67], v[38:39], v[38:39]
	v_pk_mul_f32 v[48:49], v[60:61], v[48:49]
	v_pk_mul_f32 v[34:35], v[58:59], v[58:59]
	v_pk_mul_f32 v[52:53], v[12:13], v[74:75]
	v_pk_fma_f32 v[40:41], v[22:23], v[98:99], v[40:41]
	v_pk_mul_f32 v[62:63], v[56:57], v[56:57]
	v_pk_mul_f32 v[44:45], v[12:13], v[100:101]
	v_pk_fma_f32 v[36:37], v[22:23], v[92:93], v[36:37]
	v_pk_mul_f32 v[60:61], v[48:49], v[48:49]
	v_mov_b32_e32 v64, v34
	v_mov_b32_e32 v65, v66
	v_mov_b32_e32 v66, v35
	v_pk_fma_f32 v[52:53], v[4:5], v[102:103], v[52:53]
	v_pk_mul_f32 v[40:41], v[40:41], v[54:55]
	v_pk_fma_f32 v[44:45], v[4:5], v[74:75], v[44:45]
	v_pk_mul_f32 v[46:47], v[36:37], v[46:47]
	v_pk_add_f32 v[34:35], v[64:65], v[66:67]
	v_mov_b32_e32 v64, v60
	v_mov_b32_e32 v65, v62
	v_pk_fma_f32 v[52:53], v[24:25], v[100:101], v[52:53]
	v_pk_mul_f32 v[54:55], v[40:41], v[40:41]
	v_pk_fma_f32 v[44:45], v[24:25], v[96:97], v[44:45]
	v_pk_mul_f32 v[36:37], v[46:47], v[46:47]
	v_pk_add_f32 v[34:35], v[64:65], v[34:35]
	v_mov_b32_e32 v62, v61
	v_pk_mul_f32 v[50:51], v[52:53], v[50:51]
	v_pk_mul_f32 v[42:43], v[44:45], v[42:43]
	v_pk_add_f32 v[34:35], v[62:63], v[34:35]
	v_mov_b32_e32 v60, v36
	v_mov_b32_e32 v61, v54
	v_pk_mul_f32 v[52:53], v[50:51], v[50:51]
	v_pk_mul_f32 v[44:45], v[42:43], v[42:43]
	v_pk_add_f32 v[34:35], v[60:61], v[34:35]
	v_mov_b32_e32 v54, v37
	v_pk_add_f32 v[34:35], v[54:55], v[34:35]
	v_mov_b32_e32 v36, v44
	v_mov_b32_e32 v37, v52
	v_pk_add_f32 v[34:35], v[36:37], v[34:35]
	v_mov_b32_e32 v52, v45
	v_pk_add_f32 v[34:35], v[52:53], v[34:35]
	ds_bpermute_b32 v37, v106, v35
	ds_bpermute_b32 v36, v106, v34
	v_lshl_add_u64 v[68:69], v[84:85], 0, s[4:5]
	s_lshl_b64 s[4:5], s[36:37], 11
	s_add_u32 s26, s26, 0x2000
	s_addc_u32 s27, s27, 0
	s_waitcnt lgkmcnt(0)
	v_pk_add_f32 v[34:35], v[34:35], v[36:37]
	ds_bpermute_b32 v37, v107, v35
	ds_bpermute_b32 v36, v107, v34
	s_add_u32 s28, s28, 0x6000
	s_addc_u32 s29, s29, 0
	s_add_u32 s30, s30, 0x2000
	s_addc_u32 s31, s31, 0
	s_waitcnt lgkmcnt(0)
	v_pk_add_f32 v[34:35], v[34:35], v[36:37]
	ds_bpermute_b32 v37, v108, v35
	ds_bpermute_b32 v36, v108, v34
	s_add_u32 s34, s34, 0x6000
	s_addc_u32 s35, s35, 0
	s_cmp_ge_i32 s24, s39
	s_waitcnt lgkmcnt(0)
	v_pk_add_f32 v[34:35], v[34:35], v[36:37]
	s_nop 0
	v_pk_fma_f32 v[44:45], v[34:35], s[46:47], v[104:105] op_sel_hi:[1,0,0]
	s_nop 0
	v_mul_f32_e32 v34, 0x4b800000, v45
	v_cmp_gt_f32_e64 s[40:41], s10, v45
	v_cmp_gt_f32_e32 vcc, s10, v44
	s_nop 0
	v_cndmask_b32_e64 v34, v45, v34, s[40:41]
	v_rsq_f32_e32 v34, v34
	s_nop 0
	v_mul_f32_e32 v35, 0x45800000, v34
	v_cndmask_b32_e64 v52, v34, v35, s[40:41]
	v_pk_mul_f32 v[34:35], v[38:39], v[52:53] op_sel_hi:[1,0]
	v_pk_mul_f32 v[36:37], v[56:57], v[52:53] op_sel_hi:[1,0]
	v_pk_mul_f32 v[34:35], v[30:31], v[34:35]
	v_pk_mul_f32 v[36:37], v[32:33], v[36:37]
	v_cvt_pk_bf16_f32 v34, v34, v35
	v_cvt_pk_bf16_f32 v35, v36, v37
	v_pk_mul_f32 v[36:37], v[40:41], v[52:53] op_sel_hi:[1,0]
	v_pk_mul_f32 v[38:39], v[50:51], v[52:53] op_sel_hi:[1,0]
	v_pk_mul_f32 v[36:37], v[26:27], v[36:37]
	v_pk_mul_f32 v[38:39], v[28:29], v[38:39]
	v_cvt_pk_bf16_f32 v36, v36, v37
	v_cvt_pk_bf16_f32 v37, v38, v39
	global_store_dwordx4 v[68:69], v[34:37], off offset:1024 nt
	s_nop 1
	v_mul_f32_e32 v34, 0x4b800000, v44
	v_cndmask_b32_e32 v34, v44, v34, vcc
	v_rsq_f32_e32 v34, v34
	s_nop 0
	v_mul_f32_e32 v35, 0x45800000, v34
	v_cndmask_b32_e32 v38, v34, v35, vcc
	v_pk_mul_f32 v[34:35], v[58:59], v[38:39] op_sel_hi:[1,0]
	v_pk_mul_f32 v[36:37], v[48:49], v[38:39] op_sel_hi:[1,0]
	v_pk_mul_f32 v[34:35], v[30:31], v[34:35]
	v_pk_mul_f32 v[36:37], v[32:33], v[36:37]
	v_cvt_pk_bf16_f32 v34, v34, v35
	v_cvt_pk_bf16_f32 v35, v36, v37
	v_pk_mul_f32 v[36:37], v[46:47], v[38:39] op_sel_hi:[1,0]
	v_pk_mul_f32 v[38:39], v[42:43], v[38:39] op_sel_hi:[1,0]
	v_pk_mul_f32 v[36:37], v[26:27], v[36:37]
	v_pk_mul_f32 v[38:39], v[28:29], v[38:39]
	v_cvt_pk_bf16_f32 v36, v36, v37
	v_cvt_pk_bf16_f32 v37, v38, v39
	v_lshl_add_u64 v[38:39], v[84:85], 0, s[4:5]
	global_store_dwordx4 v[38:39], v[34:37], off offset:1024 nt
	s_cbranch_scc0 .LBB0_113

.LBB0_238:
	s_ashr_i32 s31, s30, 31
	s_lshl_b64 s[4:5], s[30:31], 2
	s_add_u32 s74, s88, s4
	s_addc_u32 s75, s89, s5
	s_cmp_lg_u64 s[88:89], 0
	v_mov_b32_e32 v2, 1.0
	s_cselect_b64 s[70:71], -1, 0
	s_cmp_eq_u64 s[88:89], 0
	v_lshlrev_b32_e32 v5, 2, v132
	v_mov_b32_e32 v3, 1.0
	s_cbranch_scc1 .LBB0_240
	global_load_dword v3, v5, s[74:75] nt
.LBB0_240:
	s_mul_i32 s4, s31, s65
	s_mul_hi_u32 s5, s30, s65
	s_add_i32 s5, s5, s4
	s_mul_i32 s4, s30, s65
	s_lshl_b64 s[4:5], s[4:5], 2
	s_add_u32 s6, s52, s4
	s_addc_u32 s7, s53, s5
	s_ashr_i32 s39, s38, 31
	s_lshl_b64 s[4:5], s[38:39], 2
	v_mul_u32_u24_e32 v0, s65, v132
	s_add_u32 s38, s6, s4
	v_or_b32_e32 v4, v0, v147
	s_addc_u32 s39, s7, s5
	v_lshlrev_b32_e32 v4, 2, v4
	global_load_dword v4, v4, s[38:39] nt
	v_cndmask_b32_e64 v6, 0, 1, s[70:71]
	v_cmp_ne_u32_e64 s[52:53], 1, v6
	s_andn2_b64 vcc, exec, s[70:71]
	s_cbranch_vccnz .LBB0_242
	global_load_dword v2, v5, s[74:75] offset:8 nt
.LBB0_242:
	s_lshl_b32 s65, s65, 1
	v_add_u32_e32 v9, s65, v0
	v_or_b32_e32 v0, v9, v147
	v_lshl_add_u64 v[6:7], v[0:1], 2, s[38:39]
	global_load_dword v6, v[6:7], off nt
	v_mov_b32_e32 v7, 1.0
	s_and_b64 vcc, exec, s[52:53]
	v_mov_b32_e32 v8, 1.0
	s_cbranch_vccnz .LBB0_244
	global_load_dword v8, v5, s[74:75] offset:16 nt
.LBB0_244:
	v_add_u32_e32 v10, s65, v9
	v_or_b32_e32 v0, v10, v147
	v_lshl_add_u64 v[12:13], v[0:1], 2, s[38:39]
	global_load_dword v9, v[12:13], off nt
	s_and_b64 vcc, exec, s[52:53]
	s_cbranch_vccnz .LBB0_246
	global_load_dword v7, v5, s[74:75] offset:24 nt
.LBB0_246:
	v_add_u32_e32 v13, s65, v10
	v_or_b32_e32 v0, v13, v147
	v_lshl_add_u64 v[10:11], v[0:1], 2, s[38:39]
	global_load_dword v10, v[10:11], off nt
	v_mov_b32_e32 v11, 1.0
	s_and_b64 vcc, exec, s[52:53]
	v_mov_b32_e32 v12, 1.0
	s_cbranch_vccnz .LBB0_248
	global_load_dword v12, v5, s[74:75] offset:32 nt
.LBB0_248:
	v_add_u32_e32 v14, s65, v13
	v_or_b32_e32 v0, v14, v147
	v_lshl_add_u64 v[16:17], v[0:1], 2, s[38:39]
	global_load_dword v13, v[16:17], off nt
	s_and_b64 vcc, exec, s[52:53]
	s_cbranch_vccnz .LBB0_250
	global_load_dword v11, v5, s[74:75] offset:40 nt
.LBB0_250:
	v_add_u32_e32 v17, s65, v14
	v_or_b32_e32 v0, v17, v147
	v_lshl_add_u64 v[14:15], v[0:1], 2, s[38:39]
	global_load_dword v14, v[14:15], off nt
	v_mov_b32_e32 v15, 1.0
	s_and_b64 vcc, exec, s[52:53]
	v_mov_b32_e32 v16, 1.0
	s_cbranch_vccnz .LBB0_252
	global_load_dword v16, v5, s[74:75] offset:48 nt
.LBB0_252:
	v_add_u32_e32 v18, s65, v17
	v_or_b32_e32 v0, v18, v147
	v_lshl_add_u64 v[20:21], v[0:1], 2, s[38:39]
	global_load_dword v17, v[20:21], off nt
	s_and_b64 vcc, exec, s[52:53]
	s_cbranch_vccnz .LBB0_254
	global_load_dword v15, v5, s[74:75] offset:56 nt
.LBB0_254:
	v_add_u32_e32 v21, s65, v18
	v_or_b32_e32 v0, v21, v147
	v_lshl_add_u64 v[18:19], v[0:1], 2, s[38:39]
	global_load_dword v18, v[18:19], off nt
	v_mov_b32_e32 v19, 1.0
	s_and_b64 vcc, exec, s[52:53]
	v_mov_b32_e32 v20, 1.0
	s_cbranch_vccnz .LBB0_256
	global_load_dword v20, v5, s[74:75] offset:64 nt
.LBB0_256:
	v_add_u32_e32 v22, s65, v21
	v_or_b32_e32 v0, v22, v147
	v_lshl_add_u64 v[24:25], v[0:1], 2, s[38:39]
	global_load_dword v21, v[24:25], off nt
	s_and_b64 vcc, exec, s[52:53]
	s_cbranch_vccnz .LBB0_258
	global_load_dword v19, v5, s[74:75] offset:72 nt
.LBB0_258:
	v_add_u32_e32 v25, s65, v22
	v_or_b32_e32 v0, v25, v147
	v_lshl_add_u64 v[22:23], v[0:1], 2, s[38:39]
	global_load_dword v22, v[22:23], off nt
	v_mov_b32_e32 v23, 1.0
	s_and_b64 vcc, exec, s[52:53]
	v_mov_b32_e32 v24, 1.0
	s_cbranch_vccnz .LBB0_260
	global_load_dword v24, v5, s[74:75] offset:80 nt
.LBB0_260:
	v_add_u32_e32 v26, s65, v25
	v_or_b32_e32 v0, v26, v147
	v_lshl_add_u64 v[28:29], v[0:1], 2, s[38:39]
	global_load_dword v25, v[28:29], off nt
	s_and_b64 vcc, exec, s[52:53]
	s_cbranch_vccnz .LBB0_262
	global_load_dword v23, v5, s[74:75] offset:88 nt
.LBB0_262:
	v_add_u32_e32 v29, s65, v26
	v_or_b32_e32 v0, v29, v147
	v_lshl_add_u64 v[26:27], v[0:1], 2, s[38:39]
	global_load_dword v26, v[26:27], off nt
	v_mov_b32_e32 v27, 1.0
	s_and_b64 vcc, exec, s[52:53]
	v_mov_b32_e32 v28, 1.0
	s_cbranch_vccnz .LBB0_264
	global_load_dword v28, v5, s[74:75] offset:96 nt
.LBB0_264:
	v_add_u32_e32 v30, s65, v29
	v_or_b32_e32 v0, v30, v147
	v_lshl_add_u64 v[32:33], v[0:1], 2, s[38:39]
	global_load_dword v29, v[32:33], off nt
	s_and_b64 vcc, exec, s[52:53]
	s_cbranch_vccnz .LBB0_266
	global_load_dword v27, v5, s[74:75] offset:104 nt
.LBB0_266:
	v_add_u32_e32 v33, s65, v30
	v_or_b32_e32 v0, v33, v147
	v_lshl_add_u64 v[30:31], v[0:1], 2, s[38:39]
	global_load_dword v30, v[30:31], off nt
	v_mov_b32_e32 v31, 1.0
	s_and_b64 vcc, exec, s[52:53]
	v_mov_b32_e32 v32, 1.0
	s_cbranch_vccnz .LBB0_268
	global_load_dword v32, v5, s[74:75] offset:112 nt
.LBB0_268:
	v_add_u32_e32 v34, s65, v33
	v_or_b32_e32 v0, v34, v147
	v_lshl_add_u64 v[36:37], v[0:1], 2, s[38:39]
	global_load_dword v33, v[36:37], off nt
	s_and_b64 vcc, exec, s[52:53]
	s_cbranch_vccnz .LBB0_270
	global_load_dword v31, v5, s[74:75] offset:120 nt
.LBB0_270:
	v_add_u32_e32 v37, s65, v34
	v_or_b32_e32 v0, v37, v147
	v_lshl_add_u64 v[34:35], v[0:1], 2, s[38:39]
	global_load_dword v34, v[34:35], off nt
	v_mov_b32_e32 v35, 1.0
	s_and_b64 vcc, exec, s[52:53]
	v_mov_b32_e32 v36, 1.0
	s_cbranch_vccnz .LBB0_272
	global_load_dword v36, v5, s[74:75] offset:128 nt
.LBB0_272:
	v_add_u32_e32 v38, s65, v37
	v_or_b32_e32 v0, v38, v147
	v_lshl_add_u64 v[40:41], v[0:1], 2, s[38:39]
	global_load_dword v37, v[40:41], off nt
	s_and_b64 vcc, exec, s[52:53]
	s_cbranch_vccnz .LBB0_274
	global_load_dword v35, v5, s[74:75] offset:136 nt
.LBB0_274:
	v_add_u32_e32 v41, s65, v38
	v_or_b32_e32 v0, v41, v147
	v_lshl_add_u64 v[38:39], v[0:1], 2, s[38:39]
	global_load_dword v38, v[38:39], off nt
	v_mov_b32_e32 v39, 1.0
	s_and_b64 vcc, exec, s[52:53]
	v_mov_b32_e32 v40, 1.0
	s_cbranch_vccnz .LBB0_276
	global_load_dword v40, v5, s[74:75] offset:144 nt
.LBB0_276:
	v_add_u32_e32 v42, s65, v41
	v_or_b32_e32 v0, v42, v147
	v_lshl_add_u64 v[44:45], v[0:1], 2, s[38:39]
	global_load_dword v41, v[44:45], off nt
	s_and_b64 vcc, exec, s[52:53]
	s_cbranch_vccnz .LBB0_278
	global_load_dword v39, v5, s[74:75] offset:152 nt
.LBB0_278:
	v_add_u32_e32 v43, s65, v42
	v_or_b32_e32 v0, v43, v147
	v_lshl_add_u64 v[44:45], v[0:1], 2, s[38:39]
	global_load_dword v42, v[44:45], off nt
	v_mov_b32_e32 v44, 1.0
	s_and_b64 vcc, exec, s[52:53]
	v_mov_b32_e32 v45, 1.0
	s_cbranch_vccnz .LBB0_280
	global_load_dword v45, v5, s[74:75] offset:160 nt
.LBB0_280:
	v_add_u32_e32 v43, s65, v43
	v_or_b32_e32 v0, v43, v147
	v_lshl_add_u64 v[46:47], v[0:1], 2, s[38:39]
	global_load_dword v47, v[46:47], off nt
	s_and_b64 vcc, exec, s[52:53]
	s_cbranch_vccnz .LBB0_282
	global_load_dword v44, v5, s[74:75] offset:168 nt
.LBB0_282:
	v_add_u32_e32 v43, s65, v43
	v_or_b32_e32 v0, v43, v147
	v_lshl_add_u64 v[48:49], v[0:1], 2, s[38:39]
	global_load_dword v49, v[48:49], off nt
	v_mov_b32_e32 v50, 1.0
	s_and_b64 vcc, exec, s[52:53]
	v_mov_b32_e32 v51, 1.0
	s_cbranch_vccnz .LBB0_284
	global_load_dword v51, v5, s[74:75] offset:176 nt
.LBB0_284:
	v_add_u32_e32 v43, s65, v43
	v_or_b32_e32 v0, v43, v147
	v_lshl_add_u64 v[52:53], v[0:1], 2, s[38:39]
	global_load_dword v52, v[52:53], off nt
	s_and_b64 vcc, exec, s[52:53]
	s_cbranch_vccnz .LBB0_286
	global_load_dword v50, v5, s[74:75] offset:184 nt
.LBB0_286:
	v_add_u32_e32 v43, s65, v43
	v_or_b32_e32 v0, v43, v147
	v_lshl_add_u64 v[54:55], v[0:1], 2, s[38:39]
	global_load_dword v56, v[54:55], off nt
	v_mov_b32_e32 v58, 1.0
	s_and_b64 vcc, exec, s[52:53]
	v_mov_b32_e32 v59, 1.0
	s_cbranch_vccnz .LBB0_288
	global_load_dword v59, v5, s[74:75] offset:192 nt
.LBB0_288:
	v_add_u32_e32 v43, s65, v43
	v_or_b32_e32 v0, v43, v147
	v_lshl_add_u64 v[54:55], v[0:1], 2, s[38:39]
	global_load_dword v60, v[54:55], off nt
	s_and_b64 vcc, exec, s[52:53]
	s_cbranch_vccnz .LBB0_290
	global_load_dword v58, v5, s[74:75] offset:200 nt
.LBB0_290:
	v_add_u32_e32 v43, s65, v43
	v_or_b32_e32 v0, v43, v147
	v_lshl_add_u64 v[54:55], v[0:1], 2, s[38:39]
	global_load_dword v112, v[54:55], off nt
	v_mov_b32_e32 v114, 1.0
	s_and_b64 vcc, exec, s[52:53]
	v_mov_b32_e32 v115, 1.0
	s_cbranch_vccnz .LBB0_292
	global_load_dword v115, v5, s[74:75] offset:208 nt
.LBB0_292:
	v_add_u32_e32 v43, s65, v43
	v_or_b32_e32 v0, v43, v147
	v_lshl_add_u64 v[54:55], v[0:1], 2, s[38:39]
	global_load_dword v116, v[54:55], off nt
	s_and_b64 vcc, exec, s[52:53]
	s_cbranch_vccnz .LBB0_294
	global_load_dword v114, v5, s[74:75] offset:216 nt
.LBB0_294:
	v_add_u32_e32 v43, s65, v43
	v_or_b32_e32 v0, v43, v147
	v_lshl_add_u64 v[54:55], v[0:1], 2, s[38:39]
	global_load_dword v120, v[54:55], off nt
	v_mov_b32_e32 v122, 1.0
	s_and_b64 vcc, exec, s[52:53]
	v_mov_b32_e32 v123, 1.0
	s_cbranch_vccnz .LBB0_296
	global_load_dword v123, v5, s[74:75] offset:224 nt
.LBB0_296:
	v_add_u32_e32 v43, s65, v43
	v_or_b32_e32 v0, v43, v147
	v_lshl_add_u64 v[54:55], v[0:1], 2, s[38:39]
	global_load_dword v124, v[54:55], off nt
	s_and_b64 vcc, exec, s[52:53]
	s_cbranch_vccnz .LBB0_298
	global_load_dword v122, v5, s[74:75] offset:232 nt
.LBB0_298:
	v_add_u32_e32 v43, s65, v43
	v_or_b32_e32 v0, v43, v147
	v_lshl_add_u64 v[54:55], v[0:1], 2, s[38:39]
	global_load_dword v128, v[54:55], off nt
	v_mov_b32_e32 v130, 1.0
	s_and_b64 vcc, exec, s[52:53]
	v_mov_b32_e32 v131, 1.0
	s_cbranch_vccnz .LBB0_300
	global_load_dword v131, v5, s[74:75] offset:240 nt
.LBB0_300:
	v_add_u32_e32 v43, s65, v43
	v_or_b32_e32 v0, v43, v147
	v_lshl_add_u64 v[54:55], v[0:1], 2, s[38:39]
	global_load_dword v141, v[54:55], off nt
	s_and_b64 vcc, exec, s[52:53]
	s_cbranch_vccnz .LBB0_302
	global_load_dword v130, v5, s[74:75] offset:248 nt
.LBB0_302:
	v_add_u32_e32 v0, s65, v43
	v_or_b32_e32 v0, v0, v147
	v_lshl_add_u64 v[54:55], v[0:1], 2, s[38:39]
	global_load_dword v161, v[54:55], off nt
	s_ashr_i32 s67, s66, 31
	s_lshl_b64 s[4:5], s[66:67], 2
	s_add_u32 s74, s78, s4
	s_addc_u32 s75, s79, s5
	s_cmp_lg_u64 s[78:79], 0
	v_mov_b32_e32 v43, 1.0
	s_cselect_b64 s[70:71], -1, 0
	s_cmp_eq_u64 s[78:79], 0
	v_mov_b32_e32 v46, 1.0
	s_cbranch_scc1 .LBB0_304
	global_load_dword v46, v5, s[74:75] nt
.LBB0_304:
	s_mul_i32 s4, s67, s59
	s_mul_hi_u32 s5, s66, s59
	s_add_i32 s5, s5, s4
	s_mul_i32 s4, s66, s59
	s_lshl_b64 s[4:5], s[4:5], 2
	s_add_u32 s6, s68, s4
	s_addc_u32 s7, s69, s5
	s_ashr_i32 s77, s76, 31
	s_lshl_b64 s[4:5], s[76:77], 2
	v_mul_u32_u24_e32 v0, s59, v132
	s_add_u32 s38, s6, s4
	v_or_b32_e32 v48, v0, v147
	s_addc_u32 s39, s7, s5
	v_lshlrev_b32_e32 v48, 2, v48
	global_load_dword v48, v48, s[38:39] nt
	v_cndmask_b32_e64 v53, 0, 1, s[70:71]
	v_cmp_ne_u32_e64 s[52:53], 1, v53
	s_andn2_b64 vcc, exec, s[70:71]
	s_cbranch_vccnz .LBB0_306
	global_load_dword v43, v5, s[74:75] offset:8 nt
.LBB0_306:
	s_lshl_b32 s59, s59, 1
	v_add_u32_e32 v57, s59, v0
	v_or_b32_e32 v0, v57, v147
	v_lshl_add_u64 v[54:55], v[0:1], 2, s[38:39]
	global_load_dword v53, v[54:55], off nt
	v_mov_b32_e32 v54, 1.0
	s_and_b64 vcc, exec, s[52:53]
	v_mov_b32_e32 v55, 1.0
	s_cbranch_vccnz .LBB0_308
	global_load_dword v55, v5, s[74:75] offset:16 nt
.LBB0_308:
	v_add_u32_e32 v61, s59, v57
	v_or_b32_e32 v0, v61, v147
	v_lshl_add_u64 v[62:63], v[0:1], 2, s[38:39]
	global_load_dword v57, v[62:63], off nt
	s_and_b64 vcc, exec, s[52:53]
	s_cbranch_vccnz .LBB0_310
	global_load_dword v54, v5, s[74:75] offset:24 nt
.LBB0_310:
	v_add_u32_e32 v113, s59, v61
	v_or_b32_e32 v0, v113, v147
	v_lshl_add_u64 v[62:63], v[0:1], 2, s[38:39]
	global_load_dword v61, v[62:63], off nt
	v_mov_b32_e32 v62, 1.0
	s_and_b64 vcc, exec, s[52:53]
	v_mov_b32_e32 v63, 1.0
	s_cbranch_vccnz .LBB0_312
	global_load_dword v63, v5, s[74:75] offset:32 nt
.LBB0_312:
	v_add_u32_e32 v117, s59, v113
	v_or_b32_e32 v0, v117, v147
	v_lshl_add_u64 v[118:119], v[0:1], 2, s[38:39]
	global_load_dword v113, v[118:119], off nt
	s_and_b64 vcc, exec, s[52:53]
	s_cbranch_vccnz .LBB0_314
	global_load_dword v62, v5, s[74:75] offset:40 nt
.LBB0_314:
	v_add_u32_e32 v121, s59, v117
	v_or_b32_e32 v0, v121, v147
	v_lshl_add_u64 v[118:119], v[0:1], 2, s[38:39]
	global_load_dword v117, v[118:119], off nt
	v_mov_b32_e32 v118, 1.0
	s_and_b64 vcc, exec, s[52:53]
	v_mov_b32_e32 v119, 1.0
	s_cbranch_vccnz .LBB0_316
	global_load_dword v119, v5, s[74:75] offset:48 nt
.LBB0_316:
	v_add_u32_e32 v125, s59, v121
	v_or_b32_e32 v0, v125, v147
	v_lshl_add_u64 v[126:127], v[0:1], 2, s[38:39]
	global_load_dword v121, v[126:127], off nt
	s_and_b64 vcc, exec, s[52:53]
	s_cbranch_vccnz .LBB0_318
	global_load_dword v118, v5, s[74:75] offset:56 nt
.LBB0_318:
	v_add_u32_e32 v129, s59, v125
	v_or_b32_e32 v0, v129, v147
	v_lshl_add_u64 v[126:127], v[0:1], 2, s[38:39]
	global_load_dword v125, v[126:127], off nt
	v_mov_b32_e32 v126, 1.0
	s_and_b64 vcc, exec, s[52:53]
	v_mov_b32_e32 v127, 1.0
	s_cbranch_vccnz .LBB0_320
	global_load_dword v127, v5, s[74:75] offset:64 nt
.LBB0_320:
	v_add_u32_e32 v143, s59, v129
	v_or_b32_e32 v0, v143, v147
	v_lshl_add_u64 v[144:145], v[0:1], 2, s[38:39]
	global_load_dword v129, v[144:145], off nt
	s_and_b64 vcc, exec, s[52:53]
	s_cbranch_vccnz .LBB0_322
	global_load_dword v126, v5, s[74:75] offset:72 nt
.LBB0_322:
	v_add_u32_e32 v162, s59, v143
	v_or_b32_e32 v0, v162, v147
	v_lshl_add_u64 v[144:145], v[0:1], 2, s[38:39]
	global_load_dword v143, v[144:145], off nt
	v_mov_b32_e32 v144, 1.0
	s_and_b64 vcc, exec, s[52:53]
	v_mov_b32_e32 v145, 1.0
	s_cbranch_vccnz .LBB0_324
	global_load_dword v145, v5, s[74:75] offset:80 nt
.LBB0_324:
	v_add_u32_e32 v163, s59, v162
	v_or_b32_e32 v0, v163, v147
	v_lshl_add_u64 v[164:165], v[0:1], 2, s[38:39]
	global_load_dword v162, v[164:165], off nt
	s_and_b64 vcc, exec, s[52:53]
	s_cbranch_vccnz .LBB0_326
	global_load_dword v144, v5, s[74:75] offset:88 nt
.LBB0_326:
	v_add_u32_e32 v166, s59, v163
	v_or_b32_e32 v0, v166, v147
	v_lshl_add_u64 v[164:165], v[0:1], 2, s[38:39]
	global_load_dword v163, v[164:165], off nt
	v_mov_b32_e32 v164, 1.0
	s_and_b64 vcc, exec, s[52:53]
	v_mov_b32_e32 v165, 1.0
	s_cbranch_vccnz .LBB0_328
	global_load_dword v165, v5, s[74:75] offset:96 nt
.LBB0_328:
	v_add_u32_e32 v167, s59, v166
	v_or_b32_e32 v0, v167, v147
	v_lshl_add_u64 v[168:169], v[0:1], 2, s[38:39]
	global_load_dword v166, v[168:169], off nt
	s_and_b64 vcc, exec, s[52:53]
	s_cbranch_vccnz .LBB0_330
	global_load_dword v164, v5, s[74:75] offset:104 nt
.LBB0_330:
	v_add_u32_e32 v170, s59, v167
	v_or_b32_e32 v0, v170, v147
	v_lshl_add_u64 v[168:169], v[0:1], 2, s[38:39]
	global_load_dword v167, v[168:169], off nt
	v_mov_b32_e32 v168, 1.0
	s_and_b64 vcc, exec, s[52:53]
	v_mov_b32_e32 v169, 1.0
	s_cbranch_vccnz .LBB0_332
	global_load_dword v169, v5, s[74:75] offset:112 nt
.LBB0_332:
	v_add_u32_e32 v171, s59, v170
	v_or_b32_e32 v0, v171, v147
	v_lshl_add_u64 v[172:173], v[0:1], 2, s[38:39]
	global_load_dword v170, v[172:173], off nt
	s_and_b64 vcc, exec, s[52:53]
	s_cbranch_vccnz .LBB0_334
	global_load_dword v168, v5, s[74:75] offset:120 nt
.LBB0_334:
	v_add_u32_e32 v174, s59, v171
	v_or_b32_e32 v0, v174, v147
	v_lshl_add_u64 v[172:173], v[0:1], 2, s[38:39]
	global_load_dword v171, v[172:173], off nt
	v_mov_b32_e32 v172, 1.0
	s_and_b64 vcc, exec, s[52:53]
	v_mov_b32_e32 v173, 1.0
	s_cbranch_vccnz .LBB0_336
	global_load_dword v173, v5, s[74:75] offset:128 nt
.LBB0_336:
	v_add_u32_e32 v175, s59, v174
	v_or_b32_e32 v0, v175, v147
	v_lshl_add_u64 v[176:177], v[0:1], 2, s[38:39]
	global_load_dword v174, v[176:177], off nt
	s_and_b64 vcc, exec, s[52:53]
	s_cbranch_vccnz .LBB0_338
	global_load_dword v172, v5, s[74:75] offset:136 nt
.LBB0_338:
	v_add_u32_e32 v178, s59, v175
	v_or_b32_e32 v0, v178, v147
	v_lshl_add_u64 v[176:177], v[0:1], 2, s[38:39]
	global_load_dword v175, v[176:177], off nt
	v_mov_b32_e32 v176, 1.0
	s_and_b64 vcc, exec, s[52:53]
	v_mov_b32_e32 v177, 1.0
	s_cbranch_vccnz .LBB0_340
	global_load_dword v177, v5, s[74:75] offset:144 nt
.LBB0_340:
	v_add_u32_e32 v179, s59, v178
	v_or_b32_e32 v0, v179, v147
	v_lshl_add_u64 v[180:181], v[0:1], 2, s[38:39]
	global_load_dword v178, v[180:181], off nt
	s_and_b64 vcc, exec, s[52:53]
	s_cbranch_vccnz .LBB0_342
	global_load_dword v176, v5, s[74:75] offset:152 nt
.LBB0_342:
	v_add_u32_e32 v182, s59, v179
	v_or_b32_e32 v0, v182, v147
	v_lshl_add_u64 v[180:181], v[0:1], 2, s[38:39]
	global_load_dword v179, v[180:181], off nt
	v_mov_b32_e32 v180, 1.0
	s_and_b64 vcc, exec, s[52:53]
	v_mov_b32_e32 v181, 1.0
	s_cbranch_vccnz .LBB0_344
	global_load_dword v181, v5, s[74:75] offset:160 nt
.LBB0_344:
	v_add_u32_e32 v183, s59, v182
	v_or_b32_e32 v0, v183, v147
	v_lshl_add_u64 v[184:185], v[0:1], 2, s[38:39]
	global_load_dword v182, v[184:185], off nt
	s_and_b64 vcc, exec, s[52:53]
	s_cbranch_vccnz .LBB0_346
	global_load_dword v180, v5, s[74:75] offset:168 nt
.LBB0_346:
	v_add_u32_e32 v186, s59, v183
	v_or_b32_e32 v0, v186, v147
	v_lshl_add_u64 v[184:185], v[0:1], 2, s[38:39]
	global_load_dword v183, v[184:185], off nt
	v_mov_b32_e32 v184, 1.0
	s_and_b64 vcc, exec, s[52:53]
	v_mov_b32_e32 v185, 1.0
	s_cbranch_vccnz .LBB0_348
	global_load_dword v185, v5, s[74:75] offset:176 nt
.LBB0_348:
	v_add_u32_e32 v187, s59, v186
	v_or_b32_e32 v0, v187, v147
	v_lshl_add_u64 v[188:189], v[0:1], 2, s[38:39]
	global_load_dword v186, v[188:189], off nt
	s_and_b64 vcc, exec, s[52:53]
	s_cbranch_vccnz .LBB0_350
	global_load_dword v184, v5, s[74:75] offset:184 nt
.LBB0_350:
	v_add_u32_e32 v190, s59, v187
	v_or_b32_e32 v0, v190, v147
	v_lshl_add_u64 v[188:189], v[0:1], 2, s[38:39]
	global_load_dword v187, v[188:189], off nt
	v_mov_b32_e32 v188, 1.0
	s_and_b64 vcc, exec, s[52:53]
	v_mov_b32_e32 v189, 1.0
	s_cbranch_vccnz .LBB0_352
	global_load_dword v189, v5, s[74:75] offset:192 nt
.LBB0_352:
	v_add_u32_e32 v191, s59, v190
	v_or_b32_e32 v0, v191, v147
	v_lshl_add_u64 v[192:193], v[0:1], 2, s[38:39]
	global_load_dword v190, v[192:193], off nt
	s_and_b64 vcc, exec, s[52:53]
	s_cbranch_vccnz .LBB0_354
	global_load_dword v188, v5, s[74:75] offset:200 nt
.LBB0_354:
	v_add_u32_e32 v194, s59, v191
	v_or_b32_e32 v0, v194, v147
	v_lshl_add_u64 v[192:193], v[0:1], 2, s[38:39]
	global_load_dword v191, v[192:193], off nt
	v_mov_b32_e32 v192, 1.0
	s_and_b64 vcc, exec, s[52:53]
	v_mov_b32_e32 v193, 1.0
	s_cbranch_vccnz .LBB0_356
	global_load_dword v193, v5, s[74:75] offset:208 nt
.LBB0_356:
	v_add_u32_e32 v195, s59, v194
	v_or_b32_e32 v0, v195, v147
	v_lshl_add_u64 v[196:197], v[0:1], 2, s[38:39]
	global_load_dword v194, v[196:197], off nt
	s_and_b64 vcc, exec, s[52:53]
	s_cbranch_vccnz .LBB0_358
	global_load_dword v192, v5, s[74:75] offset:216 nt
.LBB0_358:
	v_add_u32_e32 v198, s59, v195
	v_or_b32_e32 v0, v198, v147
	v_lshl_add_u64 v[196:197], v[0:1], 2, s[38:39]
	global_load_dword v195, v[196:197], off nt
	v_mov_b32_e32 v196, 1.0
	s_and_b64 vcc, exec, s[52:53]
	v_mov_b32_e32 v197, 1.0
	s_cbranch_vccnz .LBB0_360
	global_load_dword v197, v5, s[74:75] offset:224 nt
.LBB0_360:
	v_add_u32_e32 v198, s59, v198
	v_or_b32_e32 v0, v198, v147
	v_lshl_add_u64 v[200:201], v[0:1], 2, s[38:39]
	global_load_dword v199, v[200:201], off nt
	s_and_b64 vcc, exec, s[52:53]
	s_cbranch_vccnz .LBB0_362
	global_load_dword v196, v5, s[74:75] offset:232 nt
.LBB0_362:
	v_add_u32_e32 v202, s59, v198
	v_or_b32_e32 v0, v202, v147
	v_lshl_add_u64 v[200:201], v[0:1], 2, s[38:39]
	global_load_dword v200, v[200:201], off nt
	v_mov_b32_e32 v198, 1.0
	s_and_b64 vcc, exec, s[52:53]
	v_mov_b32_e32 v201, 1.0
	s_cbranch_vccnz .LBB0_364
	global_load_dword v201, v5, s[74:75] offset:240 nt
.LBB0_364:
	v_add_u32_e32 v203, s59, v202
	v_or_b32_e32 v0, v203, v147
	v_lshl_add_u64 v[204:205], v[0:1], 2, s[38:39]
	global_load_dword v202, v[204:205], off nt
	s_and_b64 vcc, exec, s[52:53]
	s_cbranch_vccnz .LBB0_366
	global_load_dword v198, v5, s[74:75] offset:248 nt
.LBB0_366:
	v_add_u32_e32 v0, s59, v203
	v_or_b32_e32 v0, v0, v147
	s_waitcnt vmcnt(61)
	v_mul_f32_e32 v6, v2, v6
	v_mul_f32_e32 v4, v3, v4
	v_lshl_add_u64 v[2:3], v[0:1], 2, s[38:39]
	global_load_dword v3, v[2:3], off nt
	s_waitcnt vmcnt(52)
	v_mul_f32_e32 v5, v23, v26
	v_mul_f32_e32 v19, v19, v22
	v_mul_f32_e32 v20, v20, v21
	v_mul_f32_e32 v11, v11, v14
	v_mul_f32_e32 v12, v12, v13
	v_mul_f32_e32 v7, v7, v10
	v_mul_f32_e32 v8, v8, v9
	ds_write2_b32 v160, v4, v6 offset1:66
	ds_write2_b32 v160, v8, v7 offset0:132 offset1:198
	v_add_u32_e32 v2, 0x400, v160
	v_add_u32_e32 v4, 0x800, v160
	s_waitcnt vmcnt(34)
	v_mul_f32_e32 v122, v122, v128
	v_mul_f32_e32 v123, v123, v124
	v_mul_f32_e32 v58, v58, v112
	v_mul_f32_e32 v59, v59, v60
	v_mul_f32_e32 v44, v44, v49
	v_mul_f32_e32 v45, v45, v47
	v_mul_f32_e32 v35, v35, v38
	v_mul_f32_e32 v36, v36, v37
	v_mul_f32_e32 v27, v27, v30
	v_mul_f32_e32 v28, v28, v29
	v_mul_f32_e32 v23, v24, v25
	v_mul_f32_e32 v15, v15, v18
	v_mul_f32_e32 v16, v16, v17
	ds_write2_b32 v2, v12, v11 offset0:8 offset1:74
	ds_write2_b32 v2, v16, v15 offset0:140 offset1:206
	ds_write2_b32 v4, v20, v19 offset0:16 offset1:82
	ds_write2_b32 v4, v23, v5 offset0:148 offset1:214
	v_add_u32_e32 v5, 0xc00, v160
	v_add_u32_e32 v6, 0x1000, v160
	v_add_u32_e32 v7, 0x1400, v160
	v_add_u32_e32 v8, 0x1800, v160
	v_add_u32_e32 v9, 0x1c00, v160
	s_waitcnt vmcnt(32)
	v_mul_f32_e32 v130, v130, v161
	v_mul_f32_e32 v131, v131, v141
	v_mul_f32_e32 v114, v114, v120
	v_mul_f32_e32 v115, v115, v116
	v_mul_f32_e32 v50, v50, v56
	v_mul_f32_e32 v51, v51, v52
	v_mul_f32_e32 v39, v39, v42
	v_mul_f32_e32 v40, v40, v41
	v_mul_f32_e32 v31, v31, v34
	v_mul_f32_e32 v32, v32, v33
	ds_write2_b32 v5, v28, v27 offset0:24 offset1:90
	ds_write2_b32 v5, v32, v31 offset0:156 offset1:222
	ds_write2_b32 v6, v36, v35 offset0:32 offset1:98
	ds_write2_b32 v6, v40, v39 offset0:164 offset1:230
	ds_write2_b32 v7, v45, v44 offset0:40 offset1:106
	ds_write2_b32 v7, v51, v50 offset0:172 offset1:238
	ds_write2_b32 v8, v59, v58 offset0:48 offset1:114
	ds_write2_b32 v8, v115, v114 offset0:180 offset1:246
	ds_write2_b32 v9, v123, v122 offset0:56 offset1:122
	ds_write2_b32 v9, v131, v130 offset0:188 offset1:254
	s_waitcnt lgkmcnt(0)
	ds_read2_b32 v[14:15], v152 offset0:33 offset1:41
	ds_read2_b32 v[16:17], v152 offset1:8
	ds_read2_b32 v[18:19], v152 offset0:66 offset1:74
	ds_read2_b32 v[20:21], v152 offset0:99 offset1:107
	ds_read2_b32 v[22:23], v152 offset0:132 offset1:140
	ds_read2_b32 v[24:25], v152 offset0:165 offset1:173
	ds_read2_b32 v[26:27], v152 offset0:198 offset1:206
	ds_read2_b32 v[28:29], v152 offset0:231 offset1:239
	v_add_u32_e32 v0, s19, v133
	s_waitcnt lgkmcnt(6)
	v_cvt_pk_bf16_f32 v10, v16, v14
	v_ashrrev_i32_e32 v14, 31, v0
	v_mul_lo_u32 v14, s28, v14
	v_mul_lo_u32 v16, s29, v0
	v_mad_u64_u32 v[30:31], s[4:5], s28, v0, 0
	v_add3_u32 v31, v31, v14, v16
	v_lshl_add_u64 v[30:31], v[30:31], 1, s[26:27]
	s_lshl_b64 s[4:5], s[30:31], 1
	v_lshl_add_u64 v[30:31], v[30:31], 0, s[4:5]
	v_lshlrev_b32_e32 v0, 1, v136
	s_waitcnt lgkmcnt(4)
	v_cvt_pk_bf16_f32 v11, v18, v20
	s_waitcnt lgkmcnt(2)
	v_cvt_pk_bf16_f32 v12, v22, v24
	s_waitcnt lgkmcnt(0)
	v_cvt_pk_bf16_f32 v13, v26, v28
	v_lshl_add_u64 v[30:31], v[30:31], 0, v[0:1]
	v_add_u32_e32 v14, s19, v135
	global_store_dwordx4 v[30:31], v[10:13], off nt
	s_andn2_b64 vcc, exec, s[36:37]
	s_nop 0
	v_cvt_pk_bf16_f32 v10, v17, v15
	v_ashrrev_i32_e32 v15, 31, v14
	v_mul_lo_u32 v16, s28, v15
	v_mul_lo_u32 v17, s29, v14
	v_mad_u64_u32 v[14:15], s[6:7], s28, v14, 0
	v_add3_u32 v15, v15, v16, v17
	v_lshl_add_u64 v[14:15], v[14:15], 1, s[26:27]
	v_lshl_add_u64 v[14:15], v[14:15], 0, s[4:5]
	v_cvt_pk_bf16_f32 v11, v19, v21
	v_cvt_pk_bf16_f32 v12, v23, v25
	v_cvt_pk_bf16_f32 v13, v27, v29
	v_lshl_add_u64 v[14:15], v[14:15], 0, v[0:1]
	ds_read2_b32 v[16:17], v152 offset0:16 offset1:24
	ds_read2_b32 v[18:19], v152 offset0:49 offset1:57
	ds_read2_b32 v[20:21], v152 offset0:82 offset1:90
	ds_read2_b32 v[22:23], v152 offset0:115 offset1:123
	ds_read2_b32 v[24:25], v152 offset0:148 offset1:156
	ds_read2_b32 v[26:27], v152 offset0:181 offset1:189
	ds_read2_b32 v[28:29], v152 offset0:214 offset1:222
	ds_read2_b32 v[30:31], v152 offset0:247 offset1:255
	global_store_dwordx4 v[14:15], v[10:13], off nt
	v_add_u32_e32 v14, s19, v137
	v_ashrrev_i32_e32 v15, 31, v14
	s_waitcnt lgkmcnt(6)
	v_cvt_pk_bf16_f32 v10, v16, v18
	v_mul_lo_u32 v16, s28, v15
	v_mul_lo_u32 v18, s29, v14
	v_mad_u64_u32 v[14:15], s[6:7], s28, v14, 0
	v_add3_u32 v15, v15, v16, v18
	v_lshl_add_u64 v[14:15], v[14:15], 1, s[26:27]
	v_lshl_add_u64 v[14:15], v[14:15], 0, s[4:5]
	s_waitcnt lgkmcnt(4)
	v_cvt_pk_bf16_f32 v11, v20, v22
	s_waitcnt lgkmcnt(2)
	v_cvt_pk_bf16_f32 v12, v24, v26
	s_waitcnt lgkmcnt(0)
	v_cvt_pk_bf16_f32 v13, v28, v30
	v_lshl_add_u64 v[14:15], v[14:15], 0, v[0:1]
	global_store_dwordx4 v[14:15], v[10:13], off nt
	v_add_u32_e32 v14, s19, v146
	v_ashrrev_i32_e32 v15, 31, v14
	v_cvt_pk_bf16_f32 v10, v17, v19
	v_mul_lo_u32 v16, s28, v15
	v_mul_lo_u32 v17, s29, v14
	v_mad_u64_u32 v[14:15], s[6:7], s28, v14, 0
	v_add3_u32 v15, v15, v16, v17
	v_lshl_add_u64 v[14:15], v[14:15], 1, s[26:27]
	v_lshl_add_u64 v[14:15], v[14:15], 0, s[4:5]
	v_cvt_pk_bf16_f32 v11, v21, v23
	v_cvt_pk_bf16_f32 v12, v25, v27
	v_cvt_pk_bf16_f32 v13, v29, v31
	v_lshl_add_u64 v[14:15], v[14:15], 0, v[0:1]
	global_store_dwordx4 v[14:15], v[10:13], off nt
	s_waitcnt lgkmcnt(0)
	s_cbranch_vccnz .LBB0_126
	s_waitcnt vmcnt(34)
	v_mul_f32_e32 v39, v43, v53
	v_mul_f32_e32 v40, v46, v48
	s_waitcnt vmcnt(5)
	v_mul_f32_e32 v10, v201, v202
	v_mul_f32_e32 v11, v196, v200
	v_mul_f32_e32 v12, v197, v199
	v_mul_f32_e32 v13, v192, v195
	v_mul_f32_e32 v14, v193, v194
	v_mul_f32_e32 v15, v188, v191
	v_mul_f32_e32 v16, v189, v190
	v_mul_f32_e32 v17, v184, v187
	v_mul_f32_e32 v18, v185, v186
	v_mul_f32_e32 v19, v180, v183
	v_mul_f32_e32 v20, v181, v182
	v_mul_f32_e32 v21, v176, v179
	v_mul_f32_e32 v22, v177, v178
	v_mul_f32_e32 v23, v172, v175
	v_mul_f32_e32 v24, v173, v174
	v_mul_f32_e32 v25, v168, v171
	v_mul_f32_e32 v26, v169, v170
	v_mul_f32_e32 v27, v164, v167
	v_mul_f32_e32 v28, v165, v166
	v_mul_f32_e32 v29, v144, v163
	v_mul_f32_e32 v30, v145, v162
	v_mul_f32_e32 v31, v126, v143
	v_mul_f32_e32 v32, v127, v129
	v_mul_f32_e32 v33, v118, v125
	v_mul_f32_e32 v34, v119, v121
	v_mul_f32_e32 v35, v62, v117
	v_mul_f32_e32 v36, v63, v113
	v_mul_f32_e32 v37, v54, v61
	v_mul_f32_e32 v38, v55, v57
	s_waitcnt vmcnt(4)
	v_mul_f32_e32 v3, v198, v3
	ds_write2_b32 v160, v40, v39 offset1:66
	ds_write2_b32 v160, v38, v37 offset0:132 offset1:198
	ds_write2_b32 v2, v36, v35 offset0:8 offset1:74
	ds_write2_b32 v2, v34, v33 offset0:140 offset1:206
	ds_write2_b32 v4, v32, v31 offset0:16 offset1:82
	ds_write2_b32 v4, v30, v29 offset0:148 offset1:214
	ds_write2_b32 v5, v28, v27 offset0:24 offset1:90
	ds_write2_b32 v5, v26, v25 offset0:156 offset1:222
	ds_write2_b32 v6, v24, v23 offset0:32 offset1:98
	ds_write2_b32 v6, v22, v21 offset0:164 offset1:230
	ds_write2_b32 v7, v20, v19 offset0:40 offset1:106
	ds_write2_b32 v7, v18, v17 offset0:172 offset1:238
	ds_write2_b32 v8, v16, v15 offset0:48 offset1:114
	ds_write2_b32 v8, v14, v13 offset0:180 offset1:246
	ds_write2_b32 v9, v12, v11 offset0:56 offset1:122
	ds_write2_b32 v9, v10, v3 offset0:188 offset1:254
	s_waitcnt lgkmcnt(0)
	ds_read2_b32 v[6:7], v152 offset0:33 offset1:41
	ds_read2_b32 v[8:9], v152 offset1:8
	ds_read2_b32 v[10:11], v152 offset0:66 offset1:74
	ds_read2_b32 v[12:13], v152 offset0:99 offset1:107
	ds_read2_b32 v[14:15], v152 offset0:132 offset1:140
	ds_read2_b32 v[16:17], v152 offset0:165 offset1:173
	ds_read2_b32 v[18:19], v152 offset0:198 offset1:206
	ds_read2_b32 v[20:21], v152 offset0:231 offset1:239
	s_waitcnt lgkmcnt(6)
	v_cvt_pk_bf16_f32 v2, v8, v6
	v_add_u32_e32 v6, s58, v133
	v_ashrrev_i32_e32 v8, 31, v6
	s_waitcnt lgkmcnt(4)
	v_cvt_pk_bf16_f32 v3, v10, v12
	v_mul_lo_u32 v8, s94, v8
	v_mul_lo_u32 v10, s95, v6
	v_mad_u64_u32 v[22:23], s[4:5], s94, v6, 0
	v_add3_u32 v23, v23, v8, v10
	v_lshl_add_u64 v[22:23], v[22:23], 1, s[34:35]
	s_lshl_b64 s[4:5], s[66:67], 1
	v_lshl_add_u64 v[22:23], v[22:23], 0, s[4:5]
	s_waitcnt lgkmcnt(2)
	v_cvt_pk_bf16_f32 v4, v14, v16
	s_waitcnt lgkmcnt(0)
	v_cvt_pk_bf16_f32 v5, v18, v20
	v_lshl_add_u64 v[22:23], v[22:23], 0, v[0:1]
	v_add_u32_e32 v6, s58, v135
	global_store_dwordx4 v[22:23], v[2:5], off nt
	s_nop 1
	v_cvt_pk_bf16_f32 v2, v9, v7
	v_ashrrev_i32_e32 v7, 31, v6
	v_mul_lo_u32 v8, s94, v7
	v_mul_lo_u32 v9, s95, v6
	v_mad_u64_u32 v[6:7], s[6:7], s94, v6, 0
	v_add3_u32 v7, v7, v8, v9
	v_lshl_add_u64 v[6:7], v[6:7], 1, s[34:35]
	v_lshl_add_u64 v[6:7], v[6:7], 0, s[4:5]
	v_cvt_pk_bf16_f32 v3, v11, v13
	v_cvt_pk_bf16_f32 v4, v15, v17
	v_cvt_pk_bf16_f32 v5, v19, v21
	v_lshl_add_u64 v[6:7], v[6:7], 0, v[0:1]
	ds_read2_b32 v[8:9], v152 offset0:16 offset1:24
	ds_read2_b32 v[10:11], v152 offset0:49 offset1:57
	ds_read2_b32 v[12:13], v152 offset0:82 offset1:90
	ds_read2_b32 v[14:15], v152 offset0:115 offset1:123
	ds_read2_b32 v[16:17], v152 offset0:148 offset1:156
	ds_read2_b32 v[18:19], v152 offset0:181 offset1:189
	ds_read2_b32 v[20:21], v152 offset0:214 offset1:222
	ds_read2_b32 v[22:23], v152 offset0:247 offset1:255
	global_store_dwordx4 v[6:7], v[2:5], off nt
	v_add_u32_e32 v6, s58, v137
	v_ashrrev_i32_e32 v7, 31, v6
	s_waitcnt lgkmcnt(6)
	v_cvt_pk_bf16_f32 v2, v8, v10
	v_mul_lo_u32 v8, s94, v7
	v_mul_lo_u32 v10, s95, v6
	v_mad_u64_u32 v[6:7], s[6:7], s94, v6, 0
	v_add3_u32 v7, v7, v8, v10
	v_lshl_add_u64 v[6:7], v[6:7], 1, s[34:35]
	v_lshl_add_u64 v[6:7], v[6:7], 0, s[4:5]
	s_waitcnt lgkmcnt(4)
	v_cvt_pk_bf16_f32 v3, v12, v14
	s_waitcnt lgkmcnt(2)
	v_cvt_pk_bf16_f32 v4, v16, v18
	s_waitcnt lgkmcnt(0)
	v_cvt_pk_bf16_f32 v5, v20, v22
	v_lshl_add_u64 v[6:7], v[6:7], 0, v[0:1]
	global_store_dwordx4 v[6:7], v[2:5], off nt
	v_add_u32_e32 v6, s58, v146
	v_ashrrev_i32_e32 v7, 31, v6
	v_cvt_pk_bf16_f32 v2, v9, v11
	v_mul_lo_u32 v8, s94, v7
	v_mul_lo_u32 v9, s95, v6
	v_mad_u64_u32 v[6:7], s[6:7], s94, v6, 0
	v_add3_u32 v7, v7, v8, v9
	v_lshl_add_u64 v[6:7], v[6:7], 1, s[34:35]
	v_lshl_add_u64 v[6:7], v[6:7], 0, s[4:5]
	v_cvt_pk_bf16_f32 v3, v13, v15
	v_cvt_pk_bf16_f32 v4, v17, v19
	v_cvt_pk_bf16_f32 v5, v21, v23
	v_lshl_add_u64 v[6:7], v[6:7], 0, v[0:1]
	global_store_dwordx4 v[6:7], v[2:5], off nt
	s_waitcnt lgkmcnt(0)
	s_branch .LBB0_126
